# speedup vs baseline: 1.0219x; 1.0219x over previous
; DI void topk_phase(const bf16_t* PROJ, const unsigned char* K8, const unsigned char* V8, const unsigned short* SC, bf16_t* ODSA, int c, char* smem, int bid, int nb) {
;     ...
;     const uint4 qraw0 = *(const uint4*)(PROJ + (size_t)t * NP + C_DQ + lane * 16), qraw1 = *(const uint4*)(PROJ + (size_t)t * NP + C_DQ + lane * 16 + 8);
;     __syncthreads();
;     int count = 256;
;     if (n <= 256) { sel[tid] = tid < n ? tid : 0; count = n; }
;     else {
;       const unsigned short* row = SC + (size_t)item * S;
;       unsigned key[64];
; #pragma unroll
;       for (int i = 0; i < 16; ++i) {
;         key[4 * i] = 0u; key[4 * i + 1] = 0u; key[4 * i + 2] = 0u; key[4 * i + 3] = 0u;
;         if (i * 1024 < n) {
;           const int idx = (i * 256 + tid) * 4;
;           if (idx < n) {
;             const uint2 w = *(const uint2*)(row + idx);
;             key[4 * i] = w.x & 0xffffu; key[4 * i + 1] = idx + 1 < n ? w.x >> 16 : 0u; key[4 * i + 2] = idx + 2 < n ? w.y & 0xffffu : 0u; key[4 * i + 3] = idx + 3 < n ? w.y >> 16 : 0u;
;           }
;         }
;       }
.LBB0_578:
	v_readlane_b32 s0, v251, 25
	s_add_i32 s6, s0, s2
	v_mad_i64_i32 v[4:5], s[0:1], s6, v219, v[50:51]
	global_load_dwordx4 v[0:3], v[4:5], off offset:2192
	s_nop 0
	global_load_dwordx4 v[4:7], v[4:5], off offset:2176
	s_mov_b32 s4, s2
	s_ashr_i32 s7, s6, 31
	v_writelane_b32 v251, s4, 35
	s_cmpk_gt_i32 s6, 0xff
	v_writelane_b32 v250, s6, 43
	v_writelane_b32 v251, s5, 36
	s_mov_b64 s[0:1], -1
	v_writelane_b32 v250, s7, 44
	s_waitcnt vmcnt(63) expcnt(7) lgkmcnt(15)
	s_barrier
	s_cbranch_scc0 .LBB0_1045
	v_readlane_b32 s0, v251, 35
	v_readlane_b32 s1, v251, 36
	s_mov_b32 s2, s0
	s_ashr_i32 s3, s0, 31
	v_writelane_b32 v251, s0, 35
	v_cmp_ge_i32_e32 vcc, s6, v18
	v_mov_b32_e32 v158, 0
	v_writelane_b32 v251, s1, 36
	s_lshl_b64 s[0:1], s[2:3], 15
	v_readlane_b32 s2, v248, 7
	v_readlane_b32 s3, v248, 8
	s_add_u32 s0, s2, s0
	s_addc_u32 s1, s3, s1
	v_lshl_add_u64 v[8:9], v[18:19], 1, s[0:1]
	global_load_dwordx2 v[186:187], v[8:9], off
	global_load_dwordx2 v[188:189], v[8:9], off offset:2048
	v_lshl_add_u64 v[236:237], v[22:23], 1, s[0:1]
	global_load_dwordx2 v[190:191], v[236:237], off
	v_lshl_add_u64 v[238:239], v[24:25], 1, s[0:1]
	global_load_dwordx2 v[192:193], v[238:239], off
	v_lshl_add_u64 v[236:237], v[26:27], 1, s[0:1]
	global_load_dwordx2 v[194:195], v[236:237], off
	v_lshl_add_u64 v[238:239], v[28:29], 1, s[0:1]
	global_load_dwordx2 v[196:197], v[238:239], off
	v_lshl_add_u64 v[236:237], v[30:31], 1, s[0:1]
	global_load_dwordx2 v[198:199], v[236:237], off
	v_lshl_add_u64 v[238:239], v[32:33], 1, s[0:1]
	global_load_dwordx2 v[200:201], v[238:239], off
	v_lshl_add_u64 v[236:237], v[34:35], 1, s[0:1]
	global_load_dwordx2 v[202:203], v[236:237], off
	v_lshl_add_u64 v[238:239], v[36:37], 1, s[0:1]
	global_load_dwordx2 v[204:205], v[238:239], off
	v_lshl_add_u64 v[236:237], v[38:39], 1, s[0:1]
	global_load_dwordx2 v[206:207], v[236:237], off
	v_lshl_add_u64 v[238:239], v[40:41], 1, s[0:1]
	global_load_dwordx2 v[208:209], v[238:239], off
	v_lshl_add_u64 v[236:237], v[42:43], 1, s[0:1]
	global_load_dwordx2 v[210:211], v[236:237], off
	v_lshl_add_u64 v[238:239], v[44:45], 1, s[0:1]
	global_load_dwordx2 v[212:213], v[238:239], off
	v_lshl_add_u64 v[236:237], v[46:47], 1, s[0:1]
	global_load_dwordx2 v[226:227], v[236:237], off
	v_lshl_add_u64 v[238:239], v[48:49], 1, s[0:1]
	global_load_dwordx2 v[228:229], v[238:239], off
	s_waitcnt vmcnt(0)
	v_mov_b32_e32 v163, 0
	v_mov_b32_e32 v164, 0
	v_mov_b32_e32 v165, 0
	v_mov_b32_e32 v166, 0
	s_and_saveexec_b64 s[2:3], vcc
	s_cbranch_execz .LBB0_581
	v_cmp_gt_i32_e32 vcc, s6, v18
	s_nop 0
	v_and_b32_e32 v166, 0xffff, v186
	v_cndmask_b32_sdwa v165, v185, v186, vcc dst_sel:DWORD dst_unused:UNUSED_PAD src0_sel:DWORD src1_sel:WORD_1
	v_cmp_ge_i32_e32 vcc, s6, v85
	s_nop 1
	v_cndmask_b32_sdwa v164, v185, v187, vcc dst_sel:DWORD dst_unused:UNUSED_PAD src0_sel:DWORD src1_sel:WORD_0
	v_cmp_ge_i32_e32 vcc, s6, v86
	s_nop 1
	v_cndmask_b32_sdwa v163, v185, v187, vcc dst_sel:DWORD dst_unused:UNUSED_PAD src0_sel:DWORD src1_sel:WORD_1
.LBB0_581:
	s_or_b64 exec, exec, s[2:3]
	s_cmpk_lt_u32 s6, 0x400
	s_cselect_b64 s[8:9], -1, 0
	s_cmpk_gt_u32 s6, 0x3ff
	s_cselect_b64 s[2:3], -1, 0
	v_cmp_ge_i32_e32 vcc, s6, v87
	v_writelane_b32 v252, s2, 41
	s_and_b64 s[4:5], s[2:3], vcc
	v_mov_b32_e32 v160, 0
	v_writelane_b32 v252, s3, 42
	v_mov_b32_e32 v161, 0
	v_mov_b32_e32 v162, 0
	s_and_saveexec_b64 s[2:3], s[4:5]
	s_cbranch_execz .LBB0_583
	v_cmp_gt_i32_e32 vcc, s6, v87
	s_nop 0
	v_and_b32_e32 v162, 0xffff, v188
	v_cndmask_b32_sdwa v161, v185, v188, vcc dst_sel:DWORD dst_unused:UNUSED_PAD src0_sel:DWORD src1_sel:WORD_1
	v_cmp_ge_i32_e32 vcc, s6, v88
	s_nop 1
	v_cndmask_b32_sdwa v160, v185, v189, vcc dst_sel:DWORD dst_unused:UNUSED_PAD src0_sel:DWORD src1_sel:WORD_0
	v_cmp_ge_i32_e32 vcc, s6, v89
	s_nop 1
	v_cndmask_b32_sdwa v158, v185, v189, vcc dst_sel:DWORD dst_unused:UNUSED_PAD src0_sel:DWORD src1_sel:WORD_1
.LBB0_583:
	s_or_b64 exec, exec, s[2:3]
	s_cmpk_lt_u32 s6, 0x800
	s_cselect_b64 s[10:11], -1, 0
	s_cmpk_gt_u32 s6, 0x7ff
	s_cselect_b64 s[2:3], -1, 0
	v_cmp_ge_i32_e32 vcc, s6, v22
	v_writelane_b32 v252, s2, 43
	s_and_b64 s[4:5], s[2:3], vcc
	v_mov_b32_e32 v150, 0
	v_writelane_b32 v252, s3, 44
	v_mov_b32_e32 v155, 0
	v_mov_b32_e32 v156, 0
	v_mov_b32_e32 v157, 0
	v_mov_b32_e32 v159, 0
	s_and_saveexec_b64 s[2:3], s[4:5]
	s_cbranch_execz .LBB0_585
	v_lshl_add_u64 v[8:9], v[22:23], 1, s[0:1]
	v_cmp_gt_i32_e32 vcc, s6, v22
	s_nop 0
	v_and_b32_e32 v159, 0xffff, v190
	v_cndmask_b32_sdwa v157, v185, v190, vcc dst_sel:DWORD dst_unused:UNUSED_PAD src0_sel:DWORD src1_sel:WORD_1
	v_cmp_ge_i32_e32 vcc, s6, v90
	s_nop 1
	v_cndmask_b32_sdwa v156, v185, v191, vcc dst_sel:DWORD dst_unused:UNUSED_PAD src0_sel:DWORD src1_sel:WORD_0
	v_cmp_ge_i32_e32 vcc, s6, v91
	s_nop 1
	v_cndmask_b32_sdwa v155, v185, v191, vcc dst_sel:DWORD dst_unused:UNUSED_PAD src0_sel:DWORD src1_sel:WORD_1
.LBB0_585:
	s_or_b64 exec, exec, s[2:3]
	s_cmpk_lt_u32 s6, 0xc00
	s_cselect_b64 s[12:13], -1, 0
	s_cmpk_gt_u32 s6, 0xbff
	s_cselect_b64 s[2:3], -1, 0
	v_cmp_ge_i32_e32 vcc, s6, v24
	v_writelane_b32 v251, s2, 53
	s_and_b64 s[4:5], s[2:3], vcc
	v_mov_b32_e32 v152, 0
	v_writelane_b32 v251, s3, 54
	v_mov_b32_e32 v153, 0
	v_mov_b32_e32 v154, 0
	s_and_saveexec_b64 s[2:3], s[4:5]
	s_cbranch_execz .LBB0_587
	v_lshl_add_u64 v[8:9], v[24:25], 1, s[0:1]
	v_cmp_gt_i32_e32 vcc, s6, v24
	s_nop 0
	v_and_b32_e32 v154, 0xffff, v192
	v_cndmask_b32_sdwa v153, v185, v192, vcc dst_sel:DWORD dst_unused:UNUSED_PAD src0_sel:DWORD src1_sel:WORD_1
	v_cmp_ge_i32_e32 vcc, s6, v92
	s_nop 1
	v_cndmask_b32_sdwa v152, v185, v193, vcc dst_sel:DWORD dst_unused:UNUSED_PAD src0_sel:DWORD src1_sel:WORD_0
	v_cmp_ge_i32_e32 vcc, s6, v93
	s_nop 1
	v_cndmask_b32_sdwa v150, v185, v193, vcc dst_sel:DWORD dst_unused:UNUSED_PAD src0_sel:DWORD src1_sel:WORD_1
; DI void topk_phase(const bf16_t* PROJ, const unsigned char* K8, const unsigned char* V8, const unsigned short* SC, bf16_t* ODSA, int c, char* smem, int bid, int nb) {
;     ...
;       for (int i = 0; i < 16; ++i) {
;         key[4 * i] = 0u; key[4 * i + 1] = 0u; key[4 * i + 2] = 0u; key[4 * i + 3] = 0u;
;         if (i * 1024 < n) {
;           const int idx = (i * 256 + tid) * 4;
;           if (idx < n) {
;             const uint2 w = *(const uint2*)(row + idx);
;             key[4 * i] = w.x & 0xffffu; key[4 * i + 1] = idx + 1 < n ? w.x >> 16 : 0u; key[4 * i + 2] = idx + 2 < n ? w.y & 0xffffu : 0u; key[4 * i + 3] = idx + 3 < n ? w.y >> 16 : 0u;
;           }
;         }
;       }
.LBB0_587:
	s_or_b64 exec, exec, s[2:3]
	s_cmpk_lt_u32 s6, 0x1000
	s_cselect_b64 s[14:15], -1, 0
	s_cmpk_gt_u32 s6, 0xfff
	s_cselect_b64 s[2:3], -1, 0
	v_cmp_ge_i32_e32 vcc, s6, v26
	v_writelane_b32 v251, s2, 57
	s_and_b64 s[4:5], s[2:3], vcc
	v_mov_b32_e32 v142, 0
	v_writelane_b32 v251, s3, 58
	v_mov_b32_e32 v147, 0
	v_mov_b32_e32 v148, 0
	v_mov_b32_e32 v149, 0
	v_mov_b32_e32 v151, 0
	s_and_saveexec_b64 s[2:3], s[4:5]
	s_cbranch_execz .LBB0_589
	v_lshl_add_u64 v[8:9], v[26:27], 1, s[0:1]
	v_cmp_gt_i32_e32 vcc, s6, v26
	s_nop 0
	v_and_b32_e32 v151, 0xffff, v194
	v_cndmask_b32_sdwa v149, v185, v194, vcc dst_sel:DWORD dst_unused:UNUSED_PAD src0_sel:DWORD src1_sel:WORD_1
	v_cmp_ge_i32_e32 vcc, s6, v94
	s_nop 1
	v_cndmask_b32_sdwa v148, v185, v195, vcc dst_sel:DWORD dst_unused:UNUSED_PAD src0_sel:DWORD src1_sel:WORD_0
	v_cmp_ge_i32_e32 vcc, s6, v95
	s_nop 1
	v_cndmask_b32_sdwa v147, v185, v195, vcc dst_sel:DWORD dst_unused:UNUSED_PAD src0_sel:DWORD src1_sel:WORD_1
.LBB0_589:
	s_or_b64 exec, exec, s[2:3]
	s_cmpk_lt_u32 s6, 0x1400
	s_cselect_b64 s[4:5], -1, 0
	s_cmpk_gt_u32 s6, 0x13ff
	s_cselect_b64 s[2:3], -1, 0
	v_cmp_ge_i32_e32 vcc, s6, v28
	v_writelane_b32 v252, s2, 1
	s_mov_b64 s[24:25], s[6:7]
	s_and_b64 s[6:7], s[2:3], vcc
	v_writelane_b32 v252, s3, 2
	v_mov_b32_e32 v144, 0
	v_mov_b32_e32 v145, 0
	v_mov_b32_e32 v146, 0
	s_and_saveexec_b64 s[2:3], s[6:7]
	s_cbranch_execz .LBB0_591
	v_lshl_add_u64 v[8:9], v[28:29], 1, s[0:1]
	v_cmp_gt_i32_e32 vcc, s24, v28
	s_nop 0
	v_and_b32_e32 v146, 0xffff, v196
	v_cndmask_b32_sdwa v145, v185, v196, vcc dst_sel:DWORD dst_unused:UNUSED_PAD src0_sel:DWORD src1_sel:WORD_1
	v_cmp_ge_i32_e32 vcc, s24, v96
	s_nop 1
	v_cndmask_b32_sdwa v144, v185, v197, vcc dst_sel:DWORD dst_unused:UNUSED_PAD src0_sel:DWORD src1_sel:WORD_0
	v_cmp_ge_i32_e32 vcc, s24, v97
	s_nop 1
	v_cndmask_b32_sdwa v142, v185, v197, vcc dst_sel:DWORD dst_unused:UNUSED_PAD src0_sel:DWORD src1_sel:WORD_1
.LBB0_591:
	s_or_b64 exec, exec, s[2:3]
	s_cmpk_lt_u32 s24, 0x1800
	s_cselect_b64 s[2:3], -1, 0
	s_cmpk_gt_u32 s24, 0x17ff
	s_cselect_b64 s[6:7], -1, 0
	v_cmp_ge_i32_e32 vcc, s24, v30
	v_writelane_b32 v252, s6, 9
	s_and_b64 s[16:17], s[6:7], vcc
	v_mov_b32_e32 v81, 0
	v_writelane_b32 v252, s7, 10
	v_mov_b32_e32 v139, 0
	v_mov_b32_e32 v140, 0
	v_mov_b32_e32 v141, 0
	v_mov_b32_e32 v143, 0
	s_and_saveexec_b64 s[6:7], s[16:17]
	s_cbranch_execz .LBB0_593
	v_lshl_add_u64 v[8:9], v[30:31], 1, s[0:1]
	v_cmp_gt_i32_e32 vcc, s24, v30
	s_nop 0
	v_and_b32_e32 v143, 0xffff, v198
	v_cndmask_b32_sdwa v141, v185, v198, vcc dst_sel:DWORD dst_unused:UNUSED_PAD src0_sel:DWORD src1_sel:WORD_1
	v_cmp_ge_i32_e32 vcc, s24, v98
	s_nop 1
	v_cndmask_b32_sdwa v140, v185, v199, vcc dst_sel:DWORD dst_unused:UNUSED_PAD src0_sel:DWORD src1_sel:WORD_0
	v_cmp_ge_i32_e32 vcc, s24, v99
	s_nop 1
	v_cndmask_b32_sdwa v139, v185, v199, vcc dst_sel:DWORD dst_unused:UNUSED_PAD src0_sel:DWORD src1_sel:WORD_1
.LBB0_593:
	s_or_b64 exec, exec, s[6:7]
	s_cmpk_lt_u32 s24, 0x1c00
	s_cselect_b64 s[6:7], -1, 0
	s_cmpk_gt_u32 s24, 0x1bff
	s_cselect_b64 s[16:17], -1, 0
	v_cmp_ge_i32_e32 vcc, s24, v32
	v_writelane_b32 v252, s16, 19
	s_and_b64 s[18:19], s[16:17], vcc
	v_mov_b32_e32 v136, 0
	v_writelane_b32 v252, s17, 20
	v_mov_b32_e32 v137, 0
	v_mov_b32_e32 v138, 0
	s_and_saveexec_b64 s[16:17], s[18:19]
	s_cbranch_execz .LBB0_595
	v_lshl_add_u64 v[8:9], v[32:33], 1, s[0:1]
	v_cmp_gt_i32_e32 vcc, s24, v32
	s_nop 0
	v_and_b32_e32 v138, 0xffff, v200
	v_cndmask_b32_sdwa v137, v185, v200, vcc dst_sel:DWORD dst_unused:UNUSED_PAD src0_sel:DWORD src1_sel:WORD_1
	v_cmp_ge_i32_e32 vcc, s24, v100
	s_nop 1
	v_cndmask_b32_sdwa v136, v185, v201, vcc dst_sel:DWORD dst_unused:UNUSED_PAD src0_sel:DWORD src1_sel:WORD_0
	v_cmp_ge_i32_e32 vcc, s24, v101
	s_nop 1
	v_cndmask_b32_sdwa v81, v185, v201, vcc dst_sel:DWORD dst_unused:UNUSED_PAD src0_sel:DWORD src1_sel:WORD_1
.LBB0_595:
	s_or_b64 exec, exec, s[16:17]
	s_cmpk_lt_u32 s24, 0x2000
	s_cselect_b64 s[16:17], -1, 0
	s_cmpk_gt_u32 s24, 0x1fff
	s_cselect_b64 s[18:19], -1, 0
	v_cmp_ge_i32_e32 vcc, s24, v34
	v_writelane_b32 v252, s18, 27
	s_and_b64 s[20:21], s[18:19], vcc
	v_mov_b32_e32 v73, 0
	v_writelane_b32 v252, s19, 28
	v_mov_b32_e32 v78, 0
	v_mov_b32_e32 v79, 0
	v_mov_b32_e32 v80, 0
	v_mov_b32_e32 v135, 0
	s_and_saveexec_b64 s[18:19], s[20:21]
	s_cbranch_execz .LBB0_597
	v_lshl_add_u64 v[8:9], v[34:35], 1, s[0:1]
	v_cmp_gt_i32_e32 vcc, s24, v34
	s_nop 0
	v_and_b32_e32 v135, 0xffff, v202
	v_cndmask_b32_sdwa v80, v185, v202, vcc dst_sel:DWORD dst_unused:UNUSED_PAD src0_sel:DWORD src1_sel:WORD_1
	v_cmp_ge_i32_e32 vcc, s24, v102
	s_nop 1
	v_cndmask_b32_sdwa v79, v185, v203, vcc dst_sel:DWORD dst_unused:UNUSED_PAD src0_sel:DWORD src1_sel:WORD_0
	v_cmp_ge_i32_e32 vcc, s24, v103
	s_nop 1
	v_cndmask_b32_sdwa v78, v185, v203, vcc dst_sel:DWORD dst_unused:UNUSED_PAD src0_sel:DWORD src1_sel:WORD_1
.LBB0_597:
	s_or_b64 exec, exec, s[18:19]
	s_cmpk_lt_u32 s24, 0x2400
	s_cselect_b64 s[18:19], -1, 0
	s_cmpk_gt_u32 s24, 0x23ff
	s_cselect_b64 s[20:21], -1, 0
	v_cmp_ge_i32_e32 vcc, s24, v36
	v_writelane_b32 v252, s20, 35
	s_and_b64 s[22:23], s[20:21], vcc
	v_mov_b32_e32 v75, 0
	v_writelane_b32 v252, s21, 36
	v_mov_b32_e32 v76, 0
	v_mov_b32_e32 v77, 0
	s_and_saveexec_b64 s[20:21], s[22:23]
	s_cbranch_execz .LBB0_599
	v_lshl_add_u64 v[8:9], v[36:37], 1, s[0:1]
	v_cmp_gt_i32_e32 vcc, s24, v36
	s_nop 0
	v_and_b32_e32 v77, 0xffff, v204
	v_cndmask_b32_sdwa v76, v185, v204, vcc dst_sel:DWORD dst_unused:UNUSED_PAD src0_sel:DWORD src1_sel:WORD_1
	v_cmp_ge_i32_e32 vcc, s24, v104
	s_nop 1
	v_cndmask_b32_sdwa v75, v185, v205, vcc dst_sel:DWORD dst_unused:UNUSED_PAD src0_sel:DWORD src1_sel:WORD_0
	v_cmp_ge_i32_e32 vcc, s24, v105
	s_nop 1
	v_cndmask_b32_sdwa v73, v185, v205, vcc dst_sel:DWORD dst_unused:UNUSED_PAD src0_sel:DWORD src1_sel:WORD_1
; DI void topk_phase(const bf16_t* PROJ, const unsigned char* K8, const unsigned char* V8, const unsigned short* SC, bf16_t* ODSA, int c, char* smem, int bid, int nb) {
;     ...
;       for (int i = 0; i < 16; ++i) {
;         key[4 * i] = 0u; key[4 * i + 1] = 0u; key[4 * i + 2] = 0u; key[4 * i + 3] = 0u;
;         if (i * 1024 < n) {
;           const int idx = (i * 256 + tid) * 4;
;           if (idx < n) {
;             const uint2 w = *(const uint2*)(row + idx);
;             key[4 * i] = w.x & 0xffffu; key[4 * i + 1] = idx + 1 < n ? w.x >> 16 : 0u; key[4 * i + 2] = idx + 2 < n ? w.y & 0xffffu : 0u; key[4 * i + 3] = idx + 3 < n ? w.y >> 16 : 0u;
;           }
;         }
;       }
.LBB0_599:
	s_or_b64 exec, exec, s[20:21]
	s_cmpk_lt_u32 s24, 0x2800
	s_cselect_b64 s[30:31], -1, 0
	s_cmpk_gt_u32 s24, 0x27ff
	s_cselect_b64 s[20:21], -1, 0
	v_cmp_ge_i32_e32 vcc, s24, v38
	v_writelane_b32 v251, s20, 5
	s_and_b64 s[22:23], s[20:21], vcc
	v_mov_b32_e32 v64, 0
	v_writelane_b32 v251, s21, 6
	v_mov_b32_e32 v69, 0
	v_mov_b32_e32 v70, 0
	v_mov_b32_e32 v72, 0
	v_mov_b32_e32 v74, 0
	s_and_saveexec_b64 s[20:21], s[22:23]
	s_cbranch_execz .LBB0_601
	v_lshl_add_u64 v[8:9], v[38:39], 1, s[0:1]
	v_cmp_gt_i32_e32 vcc, s24, v38
	s_nop 0
	v_and_b32_e32 v74, 0xffff, v206
	v_cndmask_b32_sdwa v72, v185, v206, vcc dst_sel:DWORD dst_unused:UNUSED_PAD src0_sel:DWORD src1_sel:WORD_1
	v_cmp_ge_i32_e32 vcc, s24, v106
	s_nop 1
	v_cndmask_b32_sdwa v70, v185, v207, vcc dst_sel:DWORD dst_unused:UNUSED_PAD src0_sel:DWORD src1_sel:WORD_0
	v_cmp_ge_i32_e32 vcc, s24, v107
	s_nop 1
	v_cndmask_b32_sdwa v69, v185, v207, vcc dst_sel:DWORD dst_unused:UNUSED_PAD src0_sel:DWORD src1_sel:WORD_1
.LBB0_601:
	s_or_b64 exec, exec, s[20:21]
	s_cmpk_lt_u32 s24, 0x2c00
	s_cselect_b64 s[34:35], -1, 0
	s_cmpk_gt_u32 s24, 0x2bff
	s_cselect_b64 s[20:21], -1, 0
	v_cmp_ge_i32_e32 vcc, s24, v40
	v_writelane_b32 v251, s20, 7
	s_and_b64 s[22:23], s[20:21], vcc
	v_mov_b32_e32 v66, 0
	v_writelane_b32 v251, s21, 8
	v_mov_b32_e32 v67, 0
	v_mov_b32_e32 v68, 0
	s_and_saveexec_b64 s[20:21], s[22:23]
	s_cbranch_execz .LBB0_603
	v_lshl_add_u64 v[8:9], v[40:41], 1, s[0:1]
	v_cmp_gt_i32_e32 vcc, s24, v40
	s_nop 0
	v_and_b32_e32 v68, 0xffff, v208
	v_cndmask_b32_sdwa v67, v185, v208, vcc dst_sel:DWORD dst_unused:UNUSED_PAD src0_sel:DWORD src1_sel:WORD_1
	v_cmp_ge_i32_e32 vcc, s24, v108
	s_nop 1
	v_cndmask_b32_sdwa v66, v185, v209, vcc dst_sel:DWORD dst_unused:UNUSED_PAD src0_sel:DWORD src1_sel:WORD_0
	v_cmp_ge_i32_e32 vcc, s24, v109
	s_nop 1
	v_cndmask_b32_sdwa v64, v185, v209, vcc dst_sel:DWORD dst_unused:UNUSED_PAD src0_sel:DWORD src1_sel:WORD_1
.LBB0_603:
	s_or_b64 exec, exec, s[20:21]
	s_cmpk_lt_u32 s24, 0x3000
	s_cselect_b64 s[36:37], -1, 0
	s_cmpk_gt_u32 s24, 0x2fff
	s_cselect_b64 s[20:21], -1, 0
	v_cmp_ge_i32_e32 vcc, s24, v42
	v_writelane_b32 v251, s20, 15
	s_and_b64 s[22:23], s[20:21], vcc
	v_mov_b32_e32 v59, 0
	v_writelane_b32 v251, s21, 16
	v_mov_b32_e32 v61, 0
	v_mov_b32_e32 v62, 0
	v_mov_b32_e32 v63, 0
	v_mov_b32_e32 v65, 0
	s_and_saveexec_b64 s[20:21], s[22:23]
	s_cbranch_execz .LBB0_605
	v_lshl_add_u64 v[8:9], v[42:43], 1, s[0:1]
	v_cmp_gt_i32_e32 vcc, s24, v42
	s_nop 0
	v_and_b32_e32 v65, 0xffff, v210
	v_cndmask_b32_sdwa v63, v185, v210, vcc dst_sel:DWORD dst_unused:UNUSED_PAD src0_sel:DWORD src1_sel:WORD_1
	v_cmp_ge_i32_e32 vcc, s24, v110
	s_nop 1
	v_cndmask_b32_sdwa v62, v185, v211, vcc dst_sel:DWORD dst_unused:UNUSED_PAD src0_sel:DWORD src1_sel:WORD_0
	v_cmp_ge_i32_e32 vcc, s24, v111
	s_nop 1
	v_cndmask_b32_sdwa v61, v185, v211, vcc dst_sel:DWORD dst_unused:UNUSED_PAD src0_sel:DWORD src1_sel:WORD_1
.LBB0_605:
	s_or_b64 exec, exec, s[20:21]
	s_cmpk_lt_u32 s24, 0x3400
	s_cselect_b64 s[38:39], -1, 0
	s_cmpk_gt_u32 s24, 0x33ff
	s_cselect_b64 s[20:21], -1, 0
	v_cmp_ge_i32_e32 vcc, s24, v44
	v_writelane_b32 v251, s20, 17
	s_and_b64 s[22:23], s[20:21], vcc
	v_mov_b32_e32 v60, 0
	v_writelane_b32 v251, s21, 18
	v_mov_b32_e32 v58, 0
	v_mov_b32_e32 v57, 0
	s_and_saveexec_b64 s[20:21], s[22:23]
	s_cbranch_execz .LBB0_607
	v_lshl_add_u64 v[8:9], v[44:45], 1, s[0:1]
	v_cmp_gt_i32_e32 vcc, s24, v44
	s_nop 0
	v_and_b32_e32 v59, 0xffff, v212
	v_cndmask_b32_sdwa v60, v185, v212, vcc dst_sel:DWORD dst_unused:UNUSED_PAD src0_sel:DWORD src1_sel:WORD_1
	v_cmp_ge_i32_e32 vcc, s24, v112
	s_nop 1
	v_cndmask_b32_sdwa v58, v185, v213, vcc dst_sel:DWORD dst_unused:UNUSED_PAD src0_sel:DWORD src1_sel:WORD_0
	v_cmp_ge_i32_e32 vcc, s24, v113
	s_nop 1
	v_cndmask_b32_sdwa v57, v185, v213, vcc dst_sel:DWORD dst_unused:UNUSED_PAD src0_sel:DWORD src1_sel:WORD_1
.LBB0_607:
	s_or_b64 exec, exec, s[20:21]
	s_cmpk_lt_u32 s24, 0x3800
	s_cselect_b64 s[40:41], -1, 0
	s_cmpk_gt_u32 s24, 0x37ff
	s_cselect_b64 s[20:21], -1, 0
	v_cmp_ge_i32_e32 vcc, s24, v46
	v_writelane_b32 v251, s20, 19
	s_and_b64 s[22:23], s[20:21], vcc
	v_mov_b32_e32 v15, 0
	v_writelane_b32 v251, s21, 20
	v_mov_b32_e32 v56, 0
	v_mov_b32_e32 v55, 0
	v_mov_b32_e32 v54, 0
	v_mov_b32_e32 v53, 0
	s_and_saveexec_b64 s[20:21], s[22:23]
	s_cbranch_execz .LBB0_609
	v_lshl_add_u64 v[8:9], v[46:47], 1, s[0:1]
	v_cmp_gt_i32_e32 vcc, s24, v46
	s_nop 0
	v_and_b32_e32 v56, 0xffff, v226
	v_cndmask_b32_sdwa v55, v185, v226, vcc dst_sel:DWORD dst_unused:UNUSED_PAD src0_sel:DWORD src1_sel:WORD_1
	v_cmp_ge_i32_e32 vcc, s24, v114
	s_nop 1
	v_cndmask_b32_sdwa v54, v185, v227, vcc dst_sel:DWORD dst_unused:UNUSED_PAD src0_sel:DWORD src1_sel:WORD_0
	v_cmp_ge_i32_e32 vcc, s24, v115
	s_nop 1
	v_cndmask_b32_sdwa v53, v185, v227, vcc dst_sel:DWORD dst_unused:UNUSED_PAD src0_sel:DWORD src1_sel:WORD_1
.LBB0_609:
	s_or_b64 exec, exec, s[20:21]
	s_cmpk_lt_u32 s24, 0x3c00
	s_cselect_b64 s[42:43], -1, 0
	s_cmpk_gt_u32 s24, 0x3bff
	s_cselect_b64 s[20:21], -1, 0
	v_cmp_ge_i32_e32 vcc, s24, v48
	v_writelane_b32 v251, s20, 21
	s_and_b64 s[22:23], s[20:21], vcc
	v_mov_b32_e32 v52, 0
	v_writelane_b32 v251, s21, 22
	v_mov_b32_e32 v14, 0
	v_mov_b32_e32 v12, 0
	s_and_saveexec_b64 s[20:21], s[22:23]
	s_cbranch_execz .LBB0_611
	v_lshl_add_u64 v[8:9], v[48:49], 1, s[0:1]
	v_readlane_b32 s0, v250, 43
	v_readlane_b32 s1, v250, 44
	s_nop 0
	v_and_b32_e32 v15, 0xffff, v228
	v_cmp_gt_i32_e32 vcc, s0, v48
	s_nop 1
	v_cndmask_b32_sdwa v52, v185, v228, vcc dst_sel:DWORD dst_unused:UNUSED_PAD src0_sel:DWORD src1_sel:WORD_1
	v_cmp_ge_i32_e32 vcc, s0, v116
	s_nop 1
	v_cndmask_b32_sdwa v14, v185, v229, vcc dst_sel:DWORD dst_unused:UNUSED_PAD src0_sel:DWORD src1_sel:WORD_0
	v_cmp_ge_i32_e32 vcc, s0, v117
	s_nop 1
	v_cndmask_b32_sdwa v12, v185, v229, vcc dst_sel:DWORD dst_unused:UNUSED_PAD src0_sel:DWORD src1_sel:WORD_1

; DI void topk_phase(const bf16_t* PROJ, const unsigned char* K8, const unsigned char* V8, const unsigned short* SC, bf16_t* ODSA, int c, char* smem, int bid, int nb) {
;     ...
;     const uint4 qraw0 = *(const uint4*)(PROJ + (size_t)t * NP + C_DQ + lane * 16), qraw1 = *(const uint4*)(PROJ + (size_t)t * NP + C_DQ + lane * 16 + 8);
;     __syncthreads();
;     int count = 256;
;     if (n <= 256) { sel[tid] = tid < n ? tid : 0; count = n; }
;     else {
;       const unsigned short* row = SC + (size_t)item * S;
;       unsigned key[64];
; #pragma unroll
;       for (int i = 0; i < 16; ++i) {
;         key[4 * i] = 0u; key[4 * i + 1] = 0u; key[4 * i + 2] = 0u; key[4 * i + 3] = 0u;
;         if (i * 1024 < n) {
;           const int idx = (i * 256 + tid) * 4;
;           if (idx < n) {
;             const uint2 w = *(const uint2*)(row + idx);
;             key[4 * i] = w.x & 0xffffu; key[4 * i + 1] = idx + 1 < n ? w.x >> 16 : 0u; key[4 * i + 2] = idx + 2 < n ? w.y & 0xffffu : 0u; key[4 * i + 3] = idx + 3 < n ? w.y >> 16 : 0u;
;           }
;         }
;       }
.LBB0_1067:
	s_add_i32 s38, s80, 0x1000
	v_mad_i64_i32 v[4:5], s[0:1], s38, v219, v[34:35]
	global_load_dwordx4 v[0:3], v[4:5], off offset:2192
	s_nop 0
	global_load_dwordx4 v[4:7], v[4:5], off offset:2176
	s_ashr_i32 s39, s38, 31
	s_cmpk_gt_i32 s80, 0xf0ff
	s_mov_b64 s[0:1], -1
	s_waitcnt vmcnt(63) expcnt(7) lgkmcnt(15)
	s_barrier
	s_cbranch_scc0 .LBB0_1310
	s_ashr_i32 s81, s80, 31
	s_lshl_b64 s[0:1], s[80:81], 15
	v_readlane_b32 s2, v248, 7
	v_readlane_b32 s3, v248, 8
	s_add_u32 s0, s2, s0
	s_addc_u32 s1, s3, s1
	v_cmp_ge_i32_e32 vcc, s38, v18
	v_mov_b32_e32 v57, 0
	v_lshl_add_u64 v[8:9], v[18:19], 1, s[0:1]
	global_load_dwordx2 v[186:187], v[8:9], off
	global_load_dwordx2 v[188:189], v[8:9], off offset:2048
	v_lshl_add_u64 v[236:237], v[22:23], 1, s[0:1]
	global_load_dwordx2 v[190:191], v[236:237], off
	v_lshl_add_u64 v[238:239], v[24:25], 1, s[0:1]
	global_load_dwordx2 v[192:193], v[238:239], off
	v_lshl_add_u64 v[236:237], v[26:27], 1, s[0:1]
	global_load_dwordx2 v[194:195], v[236:237], off
	v_lshl_add_u64 v[238:239], v[28:29], 1, s[0:1]
	global_load_dwordx2 v[196:197], v[238:239], off
	v_lshl_add_u64 v[236:237], v[30:31], 1, s[0:1]
	global_load_dwordx2 v[198:199], v[236:237], off
	v_lshl_add_u64 v[238:239], v[32:33], 1, s[0:1]
	global_load_dwordx2 v[200:201], v[238:239], off
	s_waitcnt vmcnt(0)
	v_mov_b32_e32 v62, 0
	v_mov_b32_e32 v63, 0
	v_mov_b32_e32 v64, 0
	v_mov_b32_e32 v65, 0
	s_and_saveexec_b64 s[2:3], vcc
	s_cbranch_execz .LBB0_1070
	v_cmp_gt_i32_e32 vcc, s38, v18
	s_nop 0
	v_and_b32_e32 v65, 0xffff, v186
	v_cndmask_b32_sdwa v64, v185, v186, vcc dst_sel:DWORD dst_unused:UNUSED_PAD src0_sel:DWORD src1_sel:WORD_1
	v_cmp_ge_i32_e32 vcc, s38, v69
	s_nop 1
	v_cndmask_b32_sdwa v63, v185, v187, vcc dst_sel:DWORD dst_unused:UNUSED_PAD src0_sel:DWORD src1_sel:WORD_0
	v_cmp_ge_i32_e32 vcc, s38, v70
	s_nop 1
	v_cndmask_b32_sdwa v62, v185, v187, vcc dst_sel:DWORD dst_unused:UNUSED_PAD src0_sel:DWORD src1_sel:WORD_1
.LBB0_1070:
	s_or_b64 exec, exec, s[2:3]
	s_cmpk_lt_u32 s38, 0x400
	s_cselect_b64 s[2:3], -1, 0
	s_cmpk_gt_u32 s38, 0x3ff
	s_cselect_b64 s[4:5], -1, 0
	v_cmp_ge_i32_e32 vcc, s38, v71
	v_writelane_b32 v250, s4, 63
	s_and_b64 s[6:7], s[4:5], vcc
	v_mov_b32_e32 v59, 0
	v_writelane_b32 v251, s5, 0
	v_mov_b32_e32 v60, 0
	v_mov_b32_e32 v61, 0
	s_and_saveexec_b64 s[4:5], s[6:7]
	s_cbranch_execz .LBB0_1072
	v_cmp_gt_i32_e32 vcc, s38, v71
	s_add_i32 s6, s80, 0xffe
	s_nop 0
	v_and_b32_e32 v61, 0xffff, v188
	v_cndmask_b32_sdwa v60, v185, v188, vcc dst_sel:DWORD dst_unused:UNUSED_PAD src0_sel:DWORD src1_sel:WORD_1
	v_cmp_ge_i32_e32 vcc, s6, v71
	s_add_i32 s6, s80, 0xffd
	s_nop 0
	v_cndmask_b32_sdwa v59, v185, v189, vcc dst_sel:DWORD dst_unused:UNUSED_PAD src0_sel:DWORD src1_sel:WORD_0
	v_cmp_ge_i32_e32 vcc, s6, v71
	s_nop 1
	v_cndmask_b32_sdwa v57, v185, v189, vcc dst_sel:DWORD dst_unused:UNUSED_PAD src0_sel:DWORD src1_sel:WORD_1
.LBB0_1072:
	s_or_b64 exec, exec, s[4:5]
	s_cmpk_lt_u32 s38, 0x800
	s_cselect_b64 s[4:5], -1, 0
	s_cmpk_gt_u32 s38, 0x7ff
	s_cselect_b64 s[6:7], -1, 0
	v_cmp_ge_i32_e32 vcc, s38, v22
	v_writelane_b32 v251, s6, 1
	s_and_b64 s[8:9], s[6:7], vcc
	s_waitcnt vmcnt(18)
	v_mov_b32_e32 v48, 0
	v_writelane_b32 v251, s7, 2
	v_mov_b32_e32 v53, 0
	v_mov_b32_e32 v54, 0
	v_mov_b32_e32 v56, 0
	v_mov_b32_e32 v58, 0
	s_and_saveexec_b64 s[6:7], s[8:9]
	s_cbranch_execz .LBB0_1074
	v_lshl_add_u64 v[8:9], v[22:23], 1, s[0:1]
	v_cmp_gt_i32_e32 vcc, s38, v22
	s_add_i32 s8, s80, 0xffe
	s_nop 0
	v_and_b32_e32 v58, 0xffff, v190
	v_cndmask_b32_sdwa v56, v185, v190, vcc dst_sel:DWORD dst_unused:UNUSED_PAD src0_sel:DWORD src1_sel:WORD_1
	v_cmp_ge_i32_e32 vcc, s8, v22
	s_add_i32 s8, s80, 0xffd
	s_nop 0
	v_cndmask_b32_sdwa v54, v185, v191, vcc dst_sel:DWORD dst_unused:UNUSED_PAD src0_sel:DWORD src1_sel:WORD_0
	v_cmp_ge_i32_e32 vcc, s8, v22
	s_nop 1
	v_cndmask_b32_sdwa v53, v185, v191, vcc dst_sel:DWORD dst_unused:UNUSED_PAD src0_sel:DWORD src1_sel:WORD_1
.LBB0_1074:
	s_or_b64 exec, exec, s[6:7]
	s_cmpk_lt_u32 s38, 0xc00
	s_cselect_b64 s[6:7], -1, 0
	s_cmpk_gt_u32 s38, 0xbff
	s_cselect_b64 s[8:9], -1, 0
	v_cmp_ge_i32_e32 vcc, s38, v24
	v_writelane_b32 v251, s8, 3
	s_and_b64 s[10:11], s[8:9], vcc
	v_mov_b32_e32 v50, 0
	v_writelane_b32 v251, s9, 4
	v_mov_b32_e32 v51, 0
	v_mov_b32_e32 v52, 0
	s_and_saveexec_b64 s[8:9], s[10:11]
	s_cbranch_execz .LBB0_1076
	v_lshl_add_u64 v[8:9], v[24:25], 1, s[0:1]
	v_cmp_gt_i32_e32 vcc, s38, v24
	s_add_i32 s10, s80, 0xffe
	s_nop 0
	v_and_b32_e32 v52, 0xffff, v192
	v_cndmask_b32_sdwa v51, v185, v192, vcc dst_sel:DWORD dst_unused:UNUSED_PAD src0_sel:DWORD src1_sel:WORD_1
	v_cmp_ge_i32_e32 vcc, s10, v24
	s_add_i32 s10, s80, 0xffd
	s_nop 0
	v_cndmask_b32_sdwa v50, v185, v193, vcc dst_sel:DWORD dst_unused:UNUSED_PAD src0_sel:DWORD src1_sel:WORD_0
	v_cmp_ge_i32_e32 vcc, s10, v24
	s_nop 1
	v_cndmask_b32_sdwa v48, v185, v193, vcc dst_sel:DWORD dst_unused:UNUSED_PAD src0_sel:DWORD src1_sel:WORD_1
; DI void topk_phase(const bf16_t* PROJ, const unsigned char* K8, const unsigned char* V8, const unsigned short* SC, bf16_t* ODSA, int c, char* smem, int bid, int nb) {
;     ...
;       for (int i = 0; i < 16; ++i) {
;         key[4 * i] = 0u; key[4 * i + 1] = 0u; key[4 * i + 2] = 0u; key[4 * i + 3] = 0u;
;         if (i * 1024 < n) {
;           const int idx = (i * 256 + tid) * 4;
;           if (idx < n) {
;             const uint2 w = *(const uint2*)(row + idx);
;             key[4 * i] = w.x & 0xffffu; key[4 * i + 1] = idx + 1 < n ? w.x >> 16 : 0u; key[4 * i + 2] = idx + 2 < n ? w.y & 0xffffu : 0u; key[4 * i + 3] = idx + 3 < n ? w.y >> 16 : 0u;
;           }
;         }
;       }
.LBB0_1076:
	s_or_b64 exec, exec, s[8:9]
	s_cmp_gt_u32 s80, 0xffffefff
	s_cselect_b64 s[8:9], -1, 0
	s_cmp_lt_u32 s80, 0xfffff000
	s_cselect_b64 s[10:11], -1, 0
	v_cmp_ge_i32_e32 vcc, s38, v26
	v_writelane_b32 v250, s10, 47
	s_and_b64 s[12:13], s[10:11], vcc
	v_mov_b32_e32 v40, 0
	v_writelane_b32 v250, s11, 48
	v_mov_b32_e32 v45, 0
	v_mov_b32_e32 v46, 0
	v_mov_b32_e32 v47, 0
	v_mov_b32_e32 v49, 0
	s_and_saveexec_b64 s[10:11], s[12:13]
	s_cbranch_execz .LBB0_1078
	v_lshl_add_u64 v[8:9], v[26:27], 1, s[0:1]
	v_cmp_gt_i32_e32 vcc, s38, v26
	s_add_i32 s12, s80, 0xffe
	s_nop 0
	v_and_b32_e32 v49, 0xffff, v194
	v_cndmask_b32_sdwa v47, v185, v194, vcc dst_sel:DWORD dst_unused:UNUSED_PAD src0_sel:DWORD src1_sel:WORD_1
	v_cmp_ge_i32_e32 vcc, s12, v26
	s_add_i32 s12, s80, 0xffd
	s_nop 0
	v_cndmask_b32_sdwa v46, v185, v195, vcc dst_sel:DWORD dst_unused:UNUSED_PAD src0_sel:DWORD src1_sel:WORD_0
	v_cmp_ge_i32_e32 vcc, s12, v26
	s_nop 1
	v_cndmask_b32_sdwa v45, v185, v195, vcc dst_sel:DWORD dst_unused:UNUSED_PAD src0_sel:DWORD src1_sel:WORD_1
.LBB0_1078:
	s_or_b64 exec, exec, s[10:11]
	s_cmpk_lt_u32 s38, 0x1400
	s_cselect_b64 s[10:11], -1, 0
	s_cmpk_gt_u32 s38, 0x13ff
	s_cselect_b64 s[12:13], -1, 0
	v_cmp_ge_i32_e32 vcc, s38, v28
	v_writelane_b32 v250, s12, 53
	s_and_b64 s[14:15], s[12:13], vcc
	v_mov_b32_e32 v42, 0
	v_writelane_b32 v250, s13, 54
	v_mov_b32_e32 v43, 0
	v_mov_b32_e32 v44, 0
	s_and_saveexec_b64 s[12:13], s[14:15]
	s_cbranch_execz .LBB0_1080
	v_lshl_add_u64 v[8:9], v[28:29], 1, s[0:1]
	v_cmp_gt_i32_e32 vcc, s38, v28
	s_add_i32 s14, s80, 0xffe
	s_nop 0
	v_and_b32_e32 v44, 0xffff, v196
	v_cndmask_b32_sdwa v43, v185, v196, vcc dst_sel:DWORD dst_unused:UNUSED_PAD src0_sel:DWORD src1_sel:WORD_1
	v_cmp_ge_i32_e32 vcc, s14, v28
	s_add_i32 s14, s80, 0xffd
	s_nop 0
	v_cndmask_b32_sdwa v42, v185, v197, vcc dst_sel:DWORD dst_unused:UNUSED_PAD src0_sel:DWORD src1_sel:WORD_0
	v_cmp_ge_i32_e32 vcc, s14, v28
	s_nop 1
	v_cndmask_b32_sdwa v40, v185, v197, vcc dst_sel:DWORD dst_unused:UNUSED_PAD src0_sel:DWORD src1_sel:WORD_1
.LBB0_1080:
	s_or_b64 exec, exec, s[12:13]
	s_cmpk_lt_u32 s38, 0x1800
	s_cselect_b64 s[12:13], -1, 0
	s_cmpk_gt_u32 s38, 0x17ff
	s_cselect_b64 s[14:15], -1, 0
	v_cmp_ge_i32_e32 vcc, s38, v30
	v_writelane_b32 v250, s14, 57
	s_and_b64 s[16:17], s[14:15], vcc
	v_mov_b32_e32 v12, 0
	v_writelane_b32 v250, s15, 58
	v_mov_b32_e32 v37, 0
	v_mov_b32_e32 v38, 0
	v_mov_b32_e32 v39, 0
	v_mov_b32_e32 v41, 0
	s_and_saveexec_b64 s[14:15], s[16:17]
	s_cbranch_execz .LBB0_1082
	v_lshl_add_u64 v[8:9], v[30:31], 1, s[0:1]
	v_cmp_gt_i32_e32 vcc, s38, v30
	s_add_i32 s16, s80, 0xffe
	s_nop 0
	v_and_b32_e32 v41, 0xffff, v198
	v_cndmask_b32_sdwa v39, v185, v198, vcc dst_sel:DWORD dst_unused:UNUSED_PAD src0_sel:DWORD src1_sel:WORD_1
	v_cmp_ge_i32_e32 vcc, s16, v30
	s_add_i32 s16, s80, 0xffd
	s_nop 0
	v_cndmask_b32_sdwa v38, v185, v199, vcc dst_sel:DWORD dst_unused:UNUSED_PAD src0_sel:DWORD src1_sel:WORD_0
	v_cmp_ge_i32_e32 vcc, s16, v30
	s_nop 1
	v_cndmask_b32_sdwa v37, v185, v199, vcc dst_sel:DWORD dst_unused:UNUSED_PAD src0_sel:DWORD src1_sel:WORD_1
.LBB0_1082:
	s_or_b64 exec, exec, s[14:15]
	s_cmpk_lt_u32 s38, 0x1c00
	s_cselect_b64 s[14:15], -1, 0
	s_cmpk_gt_u32 s38, 0x1bff
	s_cselect_b64 s[16:17], -1, 0
	v_cmp_ge_i32_e32 vcc, s38, v32
	v_writelane_b32 v250, s16, 59
	s_and_b64 s[18:19], s[16:17], vcc
	v_mov_b32_e32 v14, 0
	v_writelane_b32 v250, s17, 60
	v_mov_b32_e32 v15, 0
	v_mov_b32_e32 v36, 0
	s_and_saveexec_b64 s[16:17], s[18:19]
	s_cbranch_execz .LBB0_1084
	v_lshl_add_u64 v[8:9], v[32:33], 1, s[0:1]
	v_cmp_gt_i32_e32 vcc, s38, v32
	s_add_i32 s0, s80, 0xffe
	s_nop 0
	v_and_b32_e32 v36, 0xffff, v200
	v_cndmask_b32_sdwa v15, v185, v200, vcc dst_sel:DWORD dst_unused:UNUSED_PAD src0_sel:DWORD src1_sel:WORD_1
	v_cmp_ge_i32_e32 vcc, s0, v32
	s_add_i32 s0, s80, 0xffd
	s_nop 0
	v_cndmask_b32_sdwa v14, v185, v201, vcc dst_sel:DWORD dst_unused:UNUSED_PAD src0_sel:DWORD src1_sel:WORD_0
	v_cmp_ge_i32_e32 vcc, s0, v32
	s_nop 1
	v_cndmask_b32_sdwa v12, v185, v201, vcc dst_sel:DWORD dst_unused:UNUSED_PAD src0_sel:DWORD src1_sel:WORD_1

; DI void topk_phase(const bf16_t* PROJ, const unsigned char* K8, const unsigned char* V8, const unsigned short* SC, bf16_t* ODSA, int c, char* smem, int bid, int nb) {
;     ...
;     const uint4 qraw0 = *(const uint4*)(PROJ + (size_t)t * NP + C_DQ + lane * 16), qraw1 = *(const uint4*)(PROJ + (size_t)t * NP + C_DQ + lane * 16 + 8);
;     __syncthreads();
;     int count = 256;
;     if (n <= 256) { sel[tid] = tid < n ? tid : 0; count = n; }
;     else {
;       const unsigned short* row = SC + (size_t)item * S;
;       unsigned key[64];
; #pragma unroll
;       for (int i = 0; i < 16; ++i) {
;         key[4 * i] = 0u; key[4 * i + 1] = 0u; key[4 * i + 2] = 0u; key[4 * i + 3] = 0u;
;         if (i * 1024 < n) {
;           const int idx = (i * 256 + tid) * 4;
;           if (idx < n) {
;             const uint2 w = *(const uint2*)(row + idx);
;             key[4 * i] = w.x & 0xffffu; key[4 * i + 1] = idx + 1 < n ? w.x >> 16 : 0u; key[4 * i + 2] = idx + 2 < n ? w.y & 0xffffu : 0u; key[4 * i + 3] = idx + 3 < n ? w.y >> 16 : 0u;
;           }
;         }
;       }
.LBB0_1355:
	v_mad_i64_i32 v[4:5], s[0:1], s48, v219, v[26:27]
	global_load_dwordx4 v[0:3], v[4:5], off offset:2192
	s_nop 0
	global_load_dwordx4 v[4:7], v[4:5], off offset:2176
	s_ashr_i32 s49, s48, 31
	s_cmpk_gt_i32 s48, 0xff
	s_mov_b64 s[0:1], -1
	s_waitcnt vmcnt(63) expcnt(7) lgkmcnt(15)
	s_barrier
	s_cbranch_scc0 .LBB0_1486
	s_lshl_b64 s[0:1], s[48:49], 15
	v_readlane_b32 s2, v248, 7
	v_readlane_b32 s3, v248, 8
	s_add_u32 s0, s2, s0
	s_addc_u32 s1, s3, s1
	v_cmp_ge_i32_e32 vcc, s48, v18
	v_mov_b32_e32 v32, 0
	v_lshl_add_u64 v[8:9], v[18:19], 1, s[0:1]
	global_load_dwordx2 v[186:187], v[8:9], off
	global_load_dwordx2 v[188:189], v[8:9], off offset:2048
	v_lshl_add_u64 v[236:237], v[22:23], 1, s[0:1]
	global_load_dwordx2 v[190:191], v[236:237], off
	v_lshl_add_u64 v[238:239], v[24:25], 1, s[0:1]
	global_load_dwordx2 v[192:193], v[238:239], off
	s_waitcnt vmcnt(0)
	v_mov_b32_e32 v37, 0
	v_mov_b32_e32 v38, 0
	v_mov_b32_e32 v39, 0
	v_mov_b32_e32 v40, 0
	s_and_saveexec_b64 s[2:3], vcc
	s_cbranch_execz .LBB0_1358
	v_cmp_gt_i32_e32 vcc, s48, v18
	s_nop 0
	v_and_b32_e32 v40, 0xffff, v186
	v_cndmask_b32_sdwa v39, v185, v186, vcc dst_sel:DWORD dst_unused:UNUSED_PAD src0_sel:DWORD src1_sel:WORD_1
	v_cmp_ge_i32_e32 vcc, s48, v61
	s_nop 1
	v_cndmask_b32_sdwa v38, v185, v187, vcc dst_sel:DWORD dst_unused:UNUSED_PAD src0_sel:DWORD src1_sel:WORD_0
	v_cmp_ge_i32_e32 vcc, s48, v62
	s_nop 1
	v_cndmask_b32_sdwa v37, v185, v187, vcc dst_sel:DWORD dst_unused:UNUSED_PAD src0_sel:DWORD src1_sel:WORD_1
.LBB0_1358:
	s_or_b64 exec, exec, s[2:3]
	s_cmpk_lt_u32 s48, 0x400
	s_cselect_b64 s[2:3], -1, 0
	s_cmpk_gt_u32 s48, 0x3ff
	s_cselect_b64 s[62:63], -1, 0
	v_cmp_ge_i32_e32 vcc, s48, v63
	s_and_b64 s[6:7], s[62:63], vcc
	v_mov_b32_e32 v34, 0
	v_mov_b32_e32 v35, 0
	v_mov_b32_e32 v36, 0
	s_and_saveexec_b64 s[4:5], s[6:7]
	s_cbranch_execz .LBB0_1360
	v_cmp_gt_i32_e32 vcc, s48, v63
	s_nop 0
	v_and_b32_e32 v36, 0xffff, v188
	v_cndmask_b32_sdwa v35, v185, v188, vcc dst_sel:DWORD dst_unused:UNUSED_PAD src0_sel:DWORD src1_sel:WORD_1
	v_cmp_ge_i32_e32 vcc, s48, v64
	s_nop 1
	v_cndmask_b32_sdwa v34, v185, v189, vcc dst_sel:DWORD dst_unused:UNUSED_PAD src0_sel:DWORD src1_sel:WORD_0
	v_cmp_ge_i32_e32 vcc, s48, v65
	s_nop 1
	v_cndmask_b32_sdwa v32, v185, v189, vcc dst_sel:DWORD dst_unused:UNUSED_PAD src0_sel:DWORD src1_sel:WORD_1
.LBB0_1360:
	s_or_b64 exec, exec, s[4:5]
	s_cmpk_lt_u32 s48, 0x800
	s_cselect_b64 s[4:5], -1, 0
	s_cmpk_gt_u32 s48, 0x7ff
	s_cselect_b64 s[54:55], -1, 0
	v_cmp_ge_i32_e32 vcc, s48, v22
	s_and_b64 s[8:9], s[54:55], vcc
	v_mov_b32_e32 v12, 0
	v_mov_b32_e32 v29, 0
	v_mov_b32_e32 v30, 0
	v_mov_b32_e32 v31, 0
	v_mov_b32_e32 v33, 0
	s_and_saveexec_b64 s[6:7], s[8:9]
	s_cbranch_execz .LBB0_1362
	v_lshl_add_u64 v[8:9], v[22:23], 1, s[0:1]
	v_cmp_gt_i32_e32 vcc, s48, v22
	s_nop 0
	v_and_b32_e32 v33, 0xffff, v190
	v_cndmask_b32_sdwa v31, v185, v190, vcc dst_sel:DWORD dst_unused:UNUSED_PAD src0_sel:DWORD src1_sel:WORD_1
	v_cmp_ge_i32_e32 vcc, s48, v66
	s_nop 1
	v_cndmask_b32_sdwa v30, v185, v191, vcc dst_sel:DWORD dst_unused:UNUSED_PAD src0_sel:DWORD src1_sel:WORD_0
	v_cmp_ge_i32_e32 vcc, s48, v67
	s_nop 1
	v_cndmask_b32_sdwa v29, v185, v191, vcc dst_sel:DWORD dst_unused:UNUSED_PAD src0_sel:DWORD src1_sel:WORD_1
.LBB0_1362:
	s_or_b64 exec, exec, s[6:7]
	s_cmpk_lt_u32 s48, 0xc00
	s_cselect_b64 s[6:7], -1, 0
	s_cmpk_gt_u32 s48, 0xbff
	s_cselect_b64 s[50:51], -1, 0
	v_cmp_ge_i32_e32 vcc, s48, v24
	s_and_b64 s[10:11], s[50:51], vcc
	v_mov_b32_e32 v14, 0
	v_mov_b32_e32 v15, 0
	v_mov_b32_e32 v28, 0
	s_and_saveexec_b64 s[8:9], s[10:11]
	s_cbranch_execz .LBB0_1364
	v_lshl_add_u64 v[8:9], v[24:25], 1, s[0:1]
	v_cmp_gt_i32_e32 vcc, s48, v24
	s_nop 0
	v_and_b32_e32 v28, 0xffff, v192
	v_cndmask_b32_sdwa v15, v185, v192, vcc dst_sel:DWORD dst_unused:UNUSED_PAD src0_sel:DWORD src1_sel:WORD_1
	v_cmp_ge_i32_e32 vcc, s48, v68
	s_nop 1
	v_cndmask_b32_sdwa v14, v185, v193, vcc dst_sel:DWORD dst_unused:UNUSED_PAD src0_sel:DWORD src1_sel:WORD_0
	v_cmp_ge_i32_e32 vcc, s48, v69
	s_nop 1
	v_cndmask_b32_sdwa v12, v185, v193, vcc dst_sel:DWORD dst_unused:UNUSED_PAD src0_sel:DWORD src1_sel:WORD_1

; template <int DQK>
; DI void attn_phase(const bf16_t* Q, int ldq, const bf16_t* K1, int ldk1, const bf16_t* K2, int ldk2, const bf16_t* VT, int ldvt,
;                    bf16_t* O, int ldo, int nheads, int nq, int nkeys, bool causal, float scale, char* smem, int bid, int nb) {
;     ...
;   for (int it = bid; it < nitems; it += nb) {
;     const int qb = nqb - 1 - it / nheads, h = it % nheads;
;     const int q0 = qb * 128, qw = q0 + wid * 32;
.LBB0_1513:
	s_ashr_i32 s0, s2, 31
	s_lshr_b32 s0, s0, 29
	s_add_i32 s0, s2, s0
	s_lshr_b32 s3, s0, 3
	s_cmp_lt_u32 s3, 64
	s_cbranch_scc1 .Lattn_qb_keep
	s_sub_i32 s3, 0xbf, s3
.Lattn_qb_keep:
	s_and_b32 s0, s0, -8
	s_sub_i32 s4, s2, s0
	s_lshl_b32 s0, s3, 7
	v_subrev_u32_e32 v234, s0, v229
	s_mul_i32 s0, s4, 0xc0
	v_or_b32_e32 v235, v234, v228
	s_ashr_i32 s1, s0, 31
	v_lshl_add_u64 v[0:1], s[0:1], 1, v[176:177]
	s_movk_i32 s5, 0xc00
	v_or_b32_e32 v236, 16, v235
	v_mad_i64_i32 v[2:3], s[0:1], v235, s5, v[0:1]
	v_mad_i64_i32 v[0:1], s[0:1], v236, s5, v[0:1]
	global_load_dwordx4 v[4:7], v[2:3], off
	global_load_dwordx4 v[8:11], v[2:3], off offset:64
	global_load_dwordx4 v[12:15], v[2:3], off offset:128
	global_load_dwordx4 v[16:19], v[2:3], off offset:192
	global_load_dwordx4 v[20:23], v[2:3], off offset:256
	global_load_dwordx4 v[24:27], v[2:3], off offset:320
	global_load_dwordx4 v[28:31], v[0:1], off
	global_load_dwordx4 v[32:35], v[0:1], off offset:64
	global_load_dwordx4 v[36:39], v[0:1], off offset:128
	global_load_dwordx4 v[40:43], v[0:1], off offset:192
	global_load_dwordx4 v[44:47], v[0:1], off offset:256
	global_load_dwordx4 v[48:51], v[0:1], off offset:320
	s_lshl_b32 s8, s4, 7
	s_ashr_i32 s9, s8, 31
	s_lshl_b64 s[6:7], s[8:9], 1
	v_readlane_b32 s0, v248, 63
	v_mov_b32_e32 v72, v226
	s_add_u32 s10, s0, s6
	s_mov_b32 s0, 0x2aaaaaab
	v_readlane_b32 s1, v249, 0
	v_mul_hi_i32 v0, v72, s0
	v_lshrrev_b32_e32 v1, 31, v0
	v_ashrrev_i32_e32 v0, 2, v0
	v_add_u32_e32 v2, v0, v1
	v_mul_lo_u32 v0, v2, 24
	v_sub_u32_e32 v0, v72, v0
	s_addc_u32 s11, s1, s7
	v_cmp_lt_i32_e32 vcc, 15, v0
	v_ashrrev_i32_e32 v3, 31, v2
	v_lshlrev_b32_e32 v0, 3, v0
	s_and_saveexec_b64 s[0:1], vcc
	s_xor_b64 s[0:1], exec, s[0:1]
	s_cbranch_execz .LBB0_1515
	v_readlane_b32 s4, v249, 1
	v_readlane_b32 s5, v249, 2
	v_mov_b32_e32 v1, v185
	s_nop 0
	v_mov_b64_e32 v[52:53], s[4:5]
	s_movk_i32 s4, 0x4200
	v_mad_i64_i32 v[2:3], s[4:5], v2, s4, v[52:53]
	s_movk_i32 s4, 0xff00
	v_lshl_add_u64 v[0:1], v[0:1], 1, v[2:3]
	s_mov_b32 s5, -1
	v_lshl_add_u64 v[52:53], v[0:1], 0, s[4:5]
